# GU epilogue activation stores also device-scope
# speedup vs baseline: 1.0118x; 1.0118x over previous
; __device__ __forceinline__ unsigned cvt_pk_bf16(float lo, float hi) { const f32x2 v = {lo, hi}; return __builtin_bit_cast(unsigned, __builtin_convertvector(v, bf16v2)); }
;   __device__ __forceinline__ void operator()(int row, int cb, int fq, f32x4 a, f32x4 b, f32x4 c, f32x4 d) const { group(row, cb, fq, a, b); group(row, cb + 128, fq, c, d); }
;   __device__ __forceinline__ void operator()(int row, int cb, int fq, f32x4 a, f32x4 b, f32x4 c, f32x4 d) const { group(row, cb, fq, a, b); group(row, cb + 128, fq, c, d); }
;     ...
;     for (int ai = 0; ai < 2; ++ai)
; #pragma unroll
;       for (int m = 0; m < 4; ++m)
;         epi(brow + ai * HALF + wr * 64 + m * 16 + fr, bcol + wc * 32, fq, acc[ai][0][m][0], acc[ai][0][m][1], acc[ai][1][m][0], acc[ai][1][m][1]);
; __device__ __forceinline__ float silu_mul(float g, float u) { return g * __builtin_amdgcn_rcpf(1.0f + __builtin_amdgcn_exp2f(-g * LOG2E)) * u; }
;   __device__ __forceinline__ void operator()(int row, int cb, int fq, f32x4 g0, f32x4 g1, f32x4 u0, f32x4 u1) const {
;     bf16_t* p = act + (size_t)row * DFF + (cb >> 8) * 128 + (cb & 255) + fq * 8; f32x4 o0, o1;
; #pragma unroll
;     for (int j = 0; j < 4; ++j) { o0[j] = silu_mul(g0[j], u0[j]); o1[j] = silu_mul(g1[j], u1[j]); }
;     u32x4 w; w.x = cvt_pk_bf16(o0[0], o0[1]); w.y = cvt_pk_bf16(o0[2], o0[3]); w.z = cvt_pk_bf16(o1[0], o1[1]); w.w = cvt_pk_bf16(o1[2], o1[3]);
;     *(u32x4*)p = w;
.LBB0_1532:
	v_or_b32_e32 v0, s10, v140
	v_add_u32_e32 v132, v0, v141
	v_mul_f32_e32 v0, 0xbfb8aa3b, v122
	v_exp_f32_e32 v0, v0
	v_readlane_b32 s6, v254, 24
	v_readlane_b32 s7, v254, 25
	s_movk_i32 s10, 0x1600
	v_add_f32_e32 v0, 1.0, v0
	v_rcp_f32_e32 v134, v0
	v_mul_f32_e32 v0, 0xbfb8aa3b, v114
	v_exp_f32_e32 v0, v0
	s_andn2_b64 vcc, exec, s[4:5]
	v_add_f32_e32 v0, 1.0, v0
	v_rcp_f32_e32 v136, v0
	v_mul_f32_e32 v0, 0xbfb8aa3b, v123
	v_exp_f32_e32 v0, v0
	s_nop 0
	v_add_f32_e32 v0, 1.0, v0
	v_rcp_f32_e32 v135, v0
	v_mul_f32_e32 v0, 0xbfb8aa3b, v115
	v_exp_f32_e32 v0, v0
	v_pk_mul_f32 v[122:123], v[122:123], v[134:135]
	s_nop 0
	v_pk_mul_f32 v[122:123], v[122:123], v[126:127]
	v_add_f32_e32 v0, 1.0, v0
	v_rcp_f32_e32 v137, v0
	v_mul_f32_e32 v0, 0xbfb8aa3b, v124
	v_exp_f32_e32 v0, v0
	v_pk_mul_f32 v[114:115], v[114:115], v[136:137]
	s_nop 0
	v_pk_mul_f32 v[118:119], v[114:115], v[118:119]
	v_add_f32_e32 v0, 1.0, v0
	v_rcp_f32_e32 v114, v0
	v_mul_f32_e32 v0, 0xbfb8aa3b, v116
	v_exp_f32_e32 v0, v0
	v_cvt_pk_bf16_f32 v118, v118, v119
	v_add_f32_e32 v0, 1.0, v0
	v_rcp_f32_e32 v126, v0
	v_mul_f32_e32 v0, 0xbfb8aa3b, v125
	v_exp_f32_e32 v0, v0
	s_nop 0
	v_add_f32_e32 v0, 1.0, v0
	v_rcp_f32_e32 v115, v0
	v_mul_f32_e32 v0, 0xbfb8aa3b, v117
	v_exp_f32_e32 v0, v0
	v_pk_mul_f32 v[114:115], v[124:125], v[114:115]
	s_nop 0
	v_pk_mul_f32 v[124:125], v[114:115], v[128:129]
	v_add_f32_e32 v0, 1.0, v0
	v_rcp_f32_e32 v127, v0
	v_lshlrev_b32_e32 v0, 6, v131
	v_mov_b32_e32 v131, v1
	v_pk_mul_f32 v[114:115], v[116:117], v[126:127]
	s_nop 0
	v_pk_mul_f32 v[120:121], v[114:115], v[120:121]
	v_mov_b64_e32 v[114:115], s[6:7]
	v_mad_i64_i32 v[116:117], s[6:7], v132, s10, v[114:115]
	v_lshl_add_u64 v[116:117], v[116:117], 0, s[90:91]
	v_lshl_add_u64 v[116:117], v[116:117], 0, v[0:1]
	v_lshl_add_u64 v[126:127], v[116:117], 0, v[130:131]
	v_cvt_pk_bf16_f32 v116, v122, v123
	v_cvt_pk_bf16_f32 v117, v124, v125
	v_cvt_pk_bf16_f32 v119, v120, v121
	global_store_dwordx4 v[126:127], v[116:119], off sc1
	v_or_b32_e32 v120, 16, v132
	s_nop 0
	v_mul_f32_e32 v117, 0xbfb8aa3b, v98
	v_exp_f32_e32 v117, v117
	v_mul_f32_e32 v116, 0xbfb8aa3b, v106
	v_exp_f32_e32 v116, v116
	v_add_f32_e32 v117, 1.0, v117
	v_rcp_f32_e32 v118, v117
	v_mul_f32_e32 v117, 0xbfb8aa3b, v107
	v_exp_f32_e32 v117, v117
	v_add_f32_e32 v116, 1.0, v116
	v_rcp_f32_e32 v116, v116
	v_add_f32_e32 v117, 1.0, v117
	v_rcp_f32_e32 v117, v117
	s_nop 0
	v_pk_mul_f32 v[106:107], v[106:107], v[116:117]
	s_nop 0
	v_pk_mul_f32 v[106:107], v[106:107], v[110:111]
	v_mul_f32_e32 v110, 0xbfb8aa3b, v99
	v_exp_f32_e32 v110, v110
	s_nop 0
	v_add_f32_e32 v110, 1.0, v110
	v_rcp_f32_e32 v119, v110
	s_nop 0
	v_pk_mul_f32 v[98:99], v[98:99], v[118:119]
	s_nop 0
	v_pk_mul_f32 v[102:103], v[98:99], v[102:103]
	v_mul_f32_e32 v99, 0xbfb8aa3b, v100
	v_exp_f32_e32 v99, v99
	v_mul_f32_e32 v98, 0xbfb8aa3b, v108
	v_exp_f32_e32 v98, v98
	v_add_f32_e32 v99, 1.0, v99
	v_rcp_f32_e32 v110, v99
	v_mul_f32_e32 v99, 0xbfb8aa3b, v109
	v_exp_f32_e32 v99, v99
	v_add_f32_e32 v98, 1.0, v98
	v_rcp_f32_e32 v98, v98
	v_add_f32_e32 v99, 1.0, v99
	v_rcp_f32_e32 v99, v99
	s_nop 0
	v_pk_mul_f32 v[98:99], v[108:109], v[98:99]
	s_nop 0
	v_pk_mul_f32 v[108:109], v[98:99], v[112:113]
	v_mul_f32_e32 v98, 0xbfb8aa3b, v101
	v_exp_f32_e32 v98, v98
	s_nop 0
	v_add_f32_e32 v98, 1.0, v98
	v_rcp_f32_e32 v111, v98
	s_nop 0
	v_pk_mul_f32 v[98:99], v[100:101], v[110:111]
	s_nop 0
	v_pk_mul_f32 v[104:105], v[98:99], v[104:105]
	v_mad_i64_i32 v[98:99], s[6:7], v120, s10, v[114:115]
	v_lshl_add_u64 v[98:99], v[98:99], 0, s[90:91]
	v_lshl_add_u64 v[98:99], v[98:99], 0, v[0:1]
	v_lshl_add_u64 v[110:111], v[98:99], 0, v[130:131]
	v_cvt_pk_bf16_f32 v98, v106, v107
	v_cvt_pk_bf16_f32 v99, v108, v109
	v_cvt_pk_bf16_f32 v100, v102, v103
	v_cvt_pk_bf16_f32 v101, v104, v105
	global_store_dwordx4 v[110:111], v[98:101], off sc1
	v_or_b32_e32 v102, 32, v132
	s_nop 0
	v_mul_f32_e32 v99, 0xbfb8aa3b, v82
	v_exp_f32_e32 v99, v99
	v_mul_f32_e32 v98, 0xbfb8aa3b, v90
	v_exp_f32_e32 v98, v98
	v_add_f32_e32 v99, 1.0, v99
	v_rcp_f32_e32 v100, v99
	v_mul_f32_e32 v99, 0xbfb8aa3b, v91
	v_exp_f32_e32 v99, v99
	v_add_f32_e32 v98, 1.0, v98
	v_rcp_f32_e32 v98, v98
	v_add_f32_e32 v99, 1.0, v99
	v_rcp_f32_e32 v99, v99
	s_nop 0
	v_pk_mul_f32 v[90:91], v[90:91], v[98:99]
	s_nop 0
	v_pk_mul_f32 v[90:91], v[90:91], v[94:95]
	v_mul_f32_e32 v94, 0xbfb8aa3b, v83
	v_exp_f32_e32 v94, v94
	s_nop 0
	v_add_f32_e32 v94, 1.0, v94
	v_rcp_f32_e32 v101, v94
	s_nop 0
	v_pk_mul_f32 v[82:83], v[82:83], v[100:101]
	s_nop 0
	v_pk_mul_f32 v[86:87], v[82:83], v[86:87]
	v_mul_f32_e32 v83, 0xbfb8aa3b, v84
	v_exp_f32_e32 v83, v83
	v_mul_f32_e32 v82, 0xbfb8aa3b, v92
	v_exp_f32_e32 v82, v82
	v_add_f32_e32 v83, 1.0, v83
	v_rcp_f32_e32 v94, v83
	v_mul_f32_e32 v83, 0xbfb8aa3b, v93
	v_exp_f32_e32 v83, v83
	v_add_f32_e32 v82, 1.0, v82
	v_rcp_f32_e32 v82, v82
	v_add_f32_e32 v83, 1.0, v83
	v_rcp_f32_e32 v83, v83
	s_nop 0
	v_pk_mul_f32 v[82:83], v[92:93], v[82:83]
	s_nop 0
	v_pk_mul_f32 v[92:93], v[82:83], v[96:97]
	v_mul_f32_e32 v82, 0xbfb8aa3b, v85
	v_exp_f32_e32 v82, v82
	s_nop 0
	v_add_f32_e32 v82, 1.0, v82
	v_rcp_f32_e32 v95, v82
	s_nop 0
	v_pk_mul_f32 v[82:83], v[84:85], v[94:95]
	s_nop 0
	v_pk_mul_f32 v[88:89], v[82:83], v[88:89]
	v_mad_i64_i32 v[82:83], s[6:7], v102, s10, v[114:115]
	v_lshl_add_u64 v[82:83], v[82:83], 0, s[90:91]
	v_lshl_add_u64 v[82:83], v[82:83], 0, v[0:1]
	v_lshl_add_u64 v[94:95], v[82:83], 0, v[130:131]
	v_cvt_pk_bf16_f32 v82, v90, v91
	v_cvt_pk_bf16_f32 v83, v92, v93
	v_cvt_pk_bf16_f32 v84, v86, v87
	v_cvt_pk_bf16_f32 v85, v88, v89
	global_store_dwordx4 v[94:95], v[82:85], off sc1
	v_or_b32_e32 v86, 48, v132
	s_nop 0
; __device__ __forceinline__ unsigned cvt_pk_bf16(float lo, float hi) { const f32x2 v = {lo, hi}; return __builtin_bit_cast(unsigned, __builtin_convertvector(v, bf16v2)); }
;   __device__ __forceinline__ void operator()(int row, int cb, int fq, f32x4 a, f32x4 b, f32x4 c, f32x4 d) const { group(row, cb, fq, a, b); group(row, cb + 128, fq, c, d); }
;   __device__ __forceinline__ void operator()(int row, int cb, int fq, f32x4 a, f32x4 b, f32x4 c, f32x4 d) const { group(row, cb, fq, a, b); group(row, cb + 128, fq, c, d); }
;     ...
;     for (int ai = 0; ai < 2; ++ai)
; #pragma unroll
;       for (int m = 0; m < 4; ++m)
;         epi(brow + ai * HALF + wr * 64 + m * 16 + fr, bcol + wc * 32, fq, acc[ai][0][m][0], acc[ai][0][m][1], acc[ai][1][m][0], acc[ai][1][m][1]);
; __device__ __forceinline__ float silu_mul(float g, float u) { return g * __builtin_amdgcn_rcpf(1.0f + __builtin_amdgcn_exp2f(-g * LOG2E)) * u; }
;   __device__ __forceinline__ void operator()(int row, int cb, int fq, f32x4 g0, f32x4 g1, f32x4 u0, f32x4 u1) const {
;     bf16_t* p = act + (size_t)row * DFF + (cb >> 8) * 128 + (cb & 255) + fq * 8; f32x4 o0, o1;
; #pragma unroll
;     for (int j = 0; j < 4; ++j) { o0[j] = silu_mul(g0[j], u0[j]); o1[j] = silu_mul(g1[j], u1[j]); }
;     u32x4 w; w.x = cvt_pk_bf16(o0[0], o0[1]); w.y = cvt_pk_bf16(o0[2], o0[3]); w.z = cvt_pk_bf16(o1[0], o1[1]); w.w = cvt_pk_bf16(o1[2], o1[3]);
;     *(u32x4*)p = w;
	v_mul_f32_e32 v83, 0xbfb8aa3b, v66
	v_exp_f32_e32 v83, v83
	v_mul_f32_e32 v82, 0xbfb8aa3b, v74
	v_exp_f32_e32 v82, v82
	v_add_f32_e32 v83, 1.0, v83
	v_rcp_f32_e32 v84, v83
	v_mul_f32_e32 v83, 0xbfb8aa3b, v75
	v_exp_f32_e32 v83, v83
	v_add_f32_e32 v82, 1.0, v82
	v_rcp_f32_e32 v82, v82
	v_add_f32_e32 v83, 1.0, v83
	v_rcp_f32_e32 v83, v83
	s_nop 0
	v_pk_mul_f32 v[74:75], v[74:75], v[82:83]
	s_nop 0
	v_pk_mul_f32 v[74:75], v[74:75], v[78:79]
	v_mul_f32_e32 v78, 0xbfb8aa3b, v67
	v_exp_f32_e32 v78, v78
	s_nop 0
	v_add_f32_e32 v78, 1.0, v78
	v_rcp_f32_e32 v85, v78
	s_nop 0
	v_pk_mul_f32 v[66:67], v[66:67], v[84:85]
	s_nop 0
	v_pk_mul_f32 v[70:71], v[66:67], v[70:71]
	v_mul_f32_e32 v67, 0xbfb8aa3b, v68
	v_exp_f32_e32 v67, v67
	v_mul_f32_e32 v66, 0xbfb8aa3b, v76
	v_exp_f32_e32 v66, v66
	v_add_f32_e32 v67, 1.0, v67
	v_rcp_f32_e32 v78, v67
	v_mul_f32_e32 v67, 0xbfb8aa3b, v77
	v_exp_f32_e32 v67, v67
	v_add_f32_e32 v66, 1.0, v66
	v_rcp_f32_e32 v66, v66
	v_add_f32_e32 v67, 1.0, v67
	v_rcp_f32_e32 v67, v67
	s_nop 0
	v_pk_mul_f32 v[66:67], v[76:77], v[66:67]
	s_nop 0
	v_pk_mul_f32 v[76:77], v[66:67], v[80:81]
	v_mul_f32_e32 v66, 0xbfb8aa3b, v69
	v_exp_f32_e32 v66, v66
	s_nop 0
	v_add_f32_e32 v66, 1.0, v66
	v_rcp_f32_e32 v79, v66
	s_nop 0
	v_pk_mul_f32 v[66:67], v[68:69], v[78:79]
	s_nop 0
	v_pk_mul_f32 v[72:73], v[66:67], v[72:73]
	v_mad_i64_i32 v[66:67], s[6:7], v86, s10, v[114:115]
	v_lshl_add_u64 v[66:67], v[66:67], 0, s[90:91]
	v_lshl_add_u64 v[66:67], v[66:67], 0, v[0:1]
	v_lshl_add_u64 v[78:79], v[66:67], 0, v[130:131]
	v_cvt_pk_bf16_f32 v66, v74, v75
	v_cvt_pk_bf16_f32 v67, v76, v77
	v_cvt_pk_bf16_f32 v68, v70, v71
	v_cvt_pk_bf16_f32 v69, v72, v73
	global_store_dwordx4 v[78:79], v[66:69], off sc1
	v_add_u32_e32 v70, 0x80, v132
	s_nop 0
	v_mul_f32_e32 v67, 0xbfb8aa3b, v50
	v_exp_f32_e32 v67, v67
	v_mul_f32_e32 v66, 0xbfb8aa3b, v58
	v_exp_f32_e32 v66, v66
	v_add_f32_e32 v67, 1.0, v67
	v_rcp_f32_e32 v68, v67
	v_mul_f32_e32 v67, 0xbfb8aa3b, v59
	v_exp_f32_e32 v67, v67
	v_add_f32_e32 v66, 1.0, v66
	v_rcp_f32_e32 v66, v66
	v_add_f32_e32 v67, 1.0, v67
	v_rcp_f32_e32 v67, v67
	s_nop 0
	v_pk_mul_f32 v[58:59], v[58:59], v[66:67]
	s_nop 0
	v_pk_mul_f32 v[58:59], v[58:59], v[62:63]
	v_mul_f32_e32 v62, 0xbfb8aa3b, v51
	v_exp_f32_e32 v62, v62
	s_nop 0
	v_add_f32_e32 v62, 1.0, v62
	v_rcp_f32_e32 v69, v62
	s_nop 0
	v_pk_mul_f32 v[50:51], v[50:51], v[68:69]
	s_nop 0
	v_pk_mul_f32 v[54:55], v[50:51], v[54:55]
	v_mul_f32_e32 v51, 0xbfb8aa3b, v52
	v_exp_f32_e32 v51, v51
	v_mul_f32_e32 v50, 0xbfb8aa3b, v60
	v_exp_f32_e32 v50, v50
	v_add_f32_e32 v51, 1.0, v51
	v_rcp_f32_e32 v62, v51
	v_mul_f32_e32 v51, 0xbfb8aa3b, v61
	v_exp_f32_e32 v51, v51
	v_add_f32_e32 v50, 1.0, v50
	v_rcp_f32_e32 v50, v50
	v_add_f32_e32 v51, 1.0, v51
	v_rcp_f32_e32 v51, v51
	s_nop 0
	v_pk_mul_f32 v[50:51], v[60:61], v[50:51]
	s_nop 0
	v_pk_mul_f32 v[60:61], v[50:51], v[64:65]
	v_mul_f32_e32 v50, 0xbfb8aa3b, v53
	v_exp_f32_e32 v50, v50
	s_nop 0
	v_add_f32_e32 v50, 1.0, v50
	v_rcp_f32_e32 v63, v50
	s_nop 0
	v_pk_mul_f32 v[50:51], v[52:53], v[62:63]
	s_nop 0
	v_pk_mul_f32 v[56:57], v[50:51], v[56:57]
	v_mad_i64_i32 v[50:51], s[6:7], v70, s10, v[114:115]
	v_lshl_add_u64 v[50:51], v[50:51], 0, s[90:91]
	v_lshl_add_u64 v[50:51], v[50:51], 0, v[0:1]
	v_lshl_add_u64 v[62:63], v[50:51], 0, v[130:131]
	v_cvt_pk_bf16_f32 v50, v58, v59
	v_cvt_pk_bf16_f32 v51, v60, v61
	v_cvt_pk_bf16_f32 v52, v54, v55
	v_cvt_pk_bf16_f32 v53, v56, v57
	global_store_dwordx4 v[62:63], v[50:53], off sc1
	v_add_u32_e32 v54, 0x90, v132
	s_nop 0
	v_mul_f32_e32 v51, 0xbfb8aa3b, v34
	v_exp_f32_e32 v51, v51
	v_mul_f32_e32 v50, 0xbfb8aa3b, v42
	v_exp_f32_e32 v50, v50
	v_add_f32_e32 v51, 1.0, v51
	v_rcp_f32_e32 v52, v51
	v_mul_f32_e32 v51, 0xbfb8aa3b, v43
	v_exp_f32_e32 v51, v51
	v_add_f32_e32 v50, 1.0, v50
	v_rcp_f32_e32 v50, v50
	v_add_f32_e32 v51, 1.0, v51
	v_rcp_f32_e32 v51, v51
	s_nop 0
	v_pk_mul_f32 v[42:43], v[42:43], v[50:51]
	s_nop 0
	v_pk_mul_f32 v[42:43], v[42:43], v[46:47]
	v_mul_f32_e32 v46, 0xbfb8aa3b, v35
	v_exp_f32_e32 v46, v46
	s_nop 0
	v_add_f32_e32 v46, 1.0, v46
	v_rcp_f32_e32 v53, v46
	s_nop 0
	v_pk_mul_f32 v[34:35], v[34:35], v[52:53]
	s_nop 0
	v_pk_mul_f32 v[38:39], v[34:35], v[38:39]
	v_mul_f32_e32 v35, 0xbfb8aa3b, v36
	v_exp_f32_e32 v35, v35
	v_mul_f32_e32 v34, 0xbfb8aa3b, v44
	v_exp_f32_e32 v34, v34
	v_add_f32_e32 v35, 1.0, v35
	v_rcp_f32_e32 v46, v35
	v_mul_f32_e32 v35, 0xbfb8aa3b, v45
	v_exp_f32_e32 v35, v35
; __device__ __forceinline__ unsigned cvt_pk_bf16(float lo, float hi) { const f32x2 v = {lo, hi}; return __builtin_bit_cast(unsigned, __builtin_convertvector(v, bf16v2)); }
; #define WAIT_V(n) asm volatile("s_waitcnt vmcnt(" #n ")" ::: "memory")
;   __device__ __forceinline__ void operator()(int row, int cb, int fq, f32x4 a, f32x4 b, f32x4 c, f32x4 d) const { group(row, cb, fq, a, b); group(row, cb + 128, fq, c, d); }
;   __device__ __forceinline__ void operator()(int row, int cb, int fq, f32x4 a, f32x4 b, f32x4 c, f32x4 d) const { group(row, cb, fq, a, b); group(row, cb + 128, fq, c, d); }
;     ...
;   if (!have_next) { WAIT_V(0); __syncthreads(); }
; __device__ __forceinline__ float silu_mul(float g, float u) { return g * __builtin_amdgcn_rcpf(1.0f + __builtin_amdgcn_exp2f(-g * LOG2E)) * u; }
;   __device__ __forceinline__ void operator()(int row, int cb, int fq, f32x4 g0, f32x4 g1, f32x4 u0, f32x4 u1) const {
;     bf16_t* p = act + (size_t)row * DFF + (cb >> 8) * 128 + (cb & 255) + fq * 8; f32x4 o0, o1;
; #pragma unroll
;     for (int j = 0; j < 4; ++j) { o0[j] = silu_mul(g0[j], u0[j]); o1[j] = silu_mul(g1[j], u1[j]); }
;     u32x4 w; w.x = cvt_pk_bf16(o0[0], o0[1]); w.y = cvt_pk_bf16(o0[2], o0[3]); w.z = cvt_pk_bf16(o1[0], o1[1]); w.w = cvt_pk_bf16(o1[2], o1[3]);
;     *(u32x4*)p = w;
; template <class Epi>
; __device__ __forceinline__ void gemm_phase(const bf16_t* A, int lda, const bf16_t* Bt, int ldb, int M, int N, int K, Epi& epi) {
;     ...
;   for (int i = 1; have; ++i) {
;     int pm2 = 0, pn2 = 0; const bool have2 = tile_order(nM, nN, (long)i * gridDim.x + blockIdx.x, pm2, pn2);
;     gemm_tile(A, lda, Bt, ldb, K, pm * BM, pn * BM, epi, pre, have2, pm2 * BM, pn2 * BM);
;     pm = pm2; pn = pn2; have = have2; pre = true;
;   }
	v_add_f32_e32 v34, 1.0, v34
	v_rcp_f32_e32 v34, v34
	v_add_f32_e32 v35, 1.0, v35
	v_rcp_f32_e32 v35, v35
	s_nop 0
	v_pk_mul_f32 v[34:35], v[44:45], v[34:35]
	s_nop 0
	v_pk_mul_f32 v[44:45], v[34:35], v[48:49]
	v_mul_f32_e32 v34, 0xbfb8aa3b, v37
	v_exp_f32_e32 v34, v34
	s_nop 0
	v_add_f32_e32 v34, 1.0, v34
	v_rcp_f32_e32 v47, v34
	s_nop 0
	v_pk_mul_f32 v[34:35], v[36:37], v[46:47]
	s_nop 0
	v_pk_mul_f32 v[40:41], v[34:35], v[40:41]
	v_mad_i64_i32 v[34:35], s[6:7], v54, s10, v[114:115]
	v_lshl_add_u64 v[34:35], v[34:35], 0, s[90:91]
	v_lshl_add_u64 v[34:35], v[34:35], 0, v[0:1]
	v_lshl_add_u64 v[46:47], v[34:35], 0, v[130:131]
	v_cvt_pk_bf16_f32 v34, v42, v43
	v_cvt_pk_bf16_f32 v35, v44, v45
	v_cvt_pk_bf16_f32 v36, v38, v39
	v_cvt_pk_bf16_f32 v37, v40, v41
	global_store_dwordx4 v[46:47], v[34:37], off sc1
	v_add_u32_e32 v38, 0xa0, v132
	s_nop 0
	v_mul_f32_e32 v35, 0xbfb8aa3b, v18
	v_exp_f32_e32 v35, v35
	v_mul_f32_e32 v34, 0xbfb8aa3b, v26
	v_exp_f32_e32 v34, v34
	v_add_f32_e32 v35, 1.0, v35
	v_rcp_f32_e32 v36, v35
	v_mul_f32_e32 v35, 0xbfb8aa3b, v27
	v_exp_f32_e32 v35, v35
	v_add_f32_e32 v34, 1.0, v34
	v_rcp_f32_e32 v34, v34
	v_add_f32_e32 v35, 1.0, v35
	v_rcp_f32_e32 v35, v35
	s_nop 0
	v_pk_mul_f32 v[26:27], v[26:27], v[34:35]
	s_nop 0
	v_pk_mul_f32 v[26:27], v[26:27], v[30:31]
	v_mul_f32_e32 v30, 0xbfb8aa3b, v19
	v_exp_f32_e32 v30, v30
	s_nop 0
	v_add_f32_e32 v30, 1.0, v30
	v_rcp_f32_e32 v37, v30
	s_nop 0
	v_pk_mul_f32 v[18:19], v[18:19], v[36:37]
	s_nop 0
	v_pk_mul_f32 v[22:23], v[18:19], v[22:23]
	v_mul_f32_e32 v19, 0xbfb8aa3b, v20
	v_exp_f32_e32 v19, v19
	v_mul_f32_e32 v18, 0xbfb8aa3b, v28
	v_exp_f32_e32 v18, v18
	v_add_f32_e32 v19, 1.0, v19
	v_rcp_f32_e32 v30, v19
	v_mul_f32_e32 v19, 0xbfb8aa3b, v29
	v_exp_f32_e32 v19, v19
	v_add_f32_e32 v18, 1.0, v18
	v_rcp_f32_e32 v18, v18
	v_add_f32_e32 v19, 1.0, v19
	v_rcp_f32_e32 v19, v19
	s_nop 0
	v_pk_mul_f32 v[18:19], v[28:29], v[18:19]
	s_nop 0
	v_pk_mul_f32 v[28:29], v[18:19], v[32:33]
	v_mul_f32_e32 v18, 0xbfb8aa3b, v21
	v_exp_f32_e32 v18, v18
	s_nop 0
	v_add_f32_e32 v18, 1.0, v18
	v_rcp_f32_e32 v31, v18
	s_nop 0
	v_pk_mul_f32 v[18:19], v[20:21], v[30:31]
	s_nop 0
	v_pk_mul_f32 v[24:25], v[18:19], v[24:25]
	v_mad_i64_i32 v[18:19], s[6:7], v38, s10, v[114:115]
	v_lshl_add_u64 v[18:19], v[18:19], 0, s[90:91]
	v_lshl_add_u64 v[18:19], v[18:19], 0, v[0:1]
	v_lshl_add_u64 v[30:31], v[18:19], 0, v[130:131]
	v_cvt_pk_bf16_f32 v18, v26, v27
	v_cvt_pk_bf16_f32 v19, v28, v29
	v_cvt_pk_bf16_f32 v20, v22, v23
	v_cvt_pk_bf16_f32 v21, v24, v25
	global_store_dwordx4 v[30:31], v[18:21], off sc1
	v_add_u32_e32 v22, 0xb0, v132
	s_nop 0
	v_mul_f32_e32 v19, 0xbfb8aa3b, v2
	v_exp_f32_e32 v19, v19
	v_mul_f32_e32 v18, 0xbfb8aa3b, v10
	v_exp_f32_e32 v18, v18
	v_add_f32_e32 v19, 1.0, v19
	v_rcp_f32_e32 v20, v19
	v_mul_f32_e32 v19, 0xbfb8aa3b, v11
	v_exp_f32_e32 v19, v19
	v_add_f32_e32 v18, 1.0, v18
	v_rcp_f32_e32 v18, v18
	v_add_f32_e32 v19, 1.0, v19
	v_rcp_f32_e32 v19, v19
	s_nop 0
	v_pk_mul_f32 v[10:11], v[10:11], v[18:19]
	s_nop 0
	v_pk_mul_f32 v[10:11], v[10:11], v[14:15]
	v_mul_f32_e32 v14, 0xbfb8aa3b, v3
	v_exp_f32_e32 v14, v14
	s_nop 0
	v_add_f32_e32 v14, 1.0, v14
	v_rcp_f32_e32 v21, v14
	s_nop 0
	v_pk_mul_f32 v[2:3], v[2:3], v[20:21]
	s_nop 0
	v_pk_mul_f32 v[6:7], v[2:3], v[6:7]
	v_mul_f32_e32 v3, 0xbfb8aa3b, v4
	v_exp_f32_e32 v3, v3
	v_mul_f32_e32 v2, 0xbfb8aa3b, v12
	v_exp_f32_e32 v2, v2
	v_add_f32_e32 v3, 1.0, v3
	v_rcp_f32_e32 v14, v3
	v_mul_f32_e32 v3, 0xbfb8aa3b, v13
	v_exp_f32_e32 v3, v3
	v_add_f32_e32 v2, 1.0, v2
	v_rcp_f32_e32 v2, v2
	v_add_f32_e32 v3, 1.0, v3
	v_rcp_f32_e32 v3, v3
	s_nop 0
	v_pk_mul_f32 v[2:3], v[12:13], v[2:3]
	s_nop 0
	v_pk_mul_f32 v[12:13], v[2:3], v[16:17]
	v_mul_f32_e32 v2, 0xbfb8aa3b, v5
	v_exp_f32_e32 v2, v2
	s_nop 0
	v_add_f32_e32 v2, 1.0, v2
	v_rcp_f32_e32 v15, v2
	s_nop 0
	v_pk_mul_f32 v[2:3], v[4:5], v[14:15]
	s_nop 0
	v_pk_mul_f32 v[8:9], v[2:3], v[8:9]
	v_mad_i64_i32 v[2:3], s[6:7], v22, s10, v[114:115]
	v_lshl_add_u64 v[2:3], v[2:3], 0, s[90:91]
	v_lshl_add_u64 v[2:3], v[2:3], 0, v[0:1]
	v_cndmask_b32_e64 v0, 0, 1, s[4:5]
	v_lshl_add_u64 v[14:15], v[2:3], 0, v[130:131]
	v_cvt_pk_bf16_f32 v2, v10, v11
	v_cvt_pk_bf16_f32 v3, v12, v13
	v_cvt_pk_bf16_f32 v4, v6, v7
	v_cvt_pk_bf16_f32 v5, v8, v9
	v_cmp_ne_u32_e64 s[6:7], 1, v0
	global_store_dwordx4 v[14:15], v[2:5], off sc1
	s_cbranch_vccnz .LBB0_1519
	s_waitcnt vmcnt(0)
	s_waitcnt vmcnt(0) lgkmcnt(0)
	s_barrier
	s_branch .LBB0_1519
